# select passes: one static s_setprio 1 for waves 4-7 from pass-1 entry to pass-2 exit
# speedup vs baseline: 1.0100x; 1.0100x over previous
.LBB0_898:
	v_and_b32_e32 v99, 63, v186
	v_lshl_add_u32 v99, v99, 4, s96
	v_add_u32_e32 v141, s96, v73
	v_add_u32_e32 v142, s96, v75
	v_add_u32_e32 v143, s96, v120
	v_add_u32_e32 v144, s96, v121
	v_add_u32_e32 v145, s96, v122
	v_add_u32_e32 v146, s96, v123
	v_add_u32_e32 v147, s96, v124
	v_readlane_b32 s1, v252, 28
	s_nop 3
	s_cmp_lt_u32 s1, 4
	s_cbranch_scc1 .Lp1_noprio
	s_setprio 1
.Lp1_noprio:
	s_mov_b32 s0, 0
	ds_read_b128 v[176:179], v99 offset:0
	ds_read_b128 v[180:183], v99 offset:4096
	ds_read_b128 v[230:233], v99 offset:1024
	ds_read_b128 v[234:237], v99 offset:5120
	ds_read_b128 v[238:241], v99 offset:2048
	ds_read_b128 v[242:245], v99 offset:6144
	ds_read_b128 v[246:249], v99 offset:3072
	ds_read_b128 v[50:53], v99 offset:7168
	s_waitcnt lgkmcnt(7)
	v_mfma_f32_32x32x16_bf16 v[0:15], v[34:37], v[176:179], 0
	s_waitcnt lgkmcnt(6)
	v_mfma_f32_32x32x16_bf16 v[160:175], v[34:37], v[180:183], 0
	s_waitcnt vmcnt(3)
	ds_write_b128 v140, v[16:19] offset:8192
	s_add_i32 s1, s0, 5
	s_min_i32 s1, s1, s14
	v_mad_i64_i32 v[184:185], s[2:3], s1, v193, v[116:117]
	global_load_dwordx4 v[16:19], v[184:185], off
	s_waitcnt lgkmcnt(6)
	v_mfma_f32_32x32x16_bf16 v[0:15], v[38:41], v[230:233], v[0:15]
	s_waitcnt lgkmcnt(5)
	v_mfma_f32_32x32x16_bf16 v[160:175], v[38:41], v[234:237], v[160:175]
	s_waitcnt lgkmcnt(4)
	v_mfma_f32_32x32x16_bf16 v[0:15], v[42:45], v[238:241], v[0:15]
	s_waitcnt lgkmcnt(3)
	v_mfma_f32_32x32x16_bf16 v[160:175], v[42:45], v[242:245], v[160:175]
	s_waitcnt lgkmcnt(2)
	v_mfma_f32_32x32x16_bf16 v[0:15], v[46:49], v[246:249], v[0:15]
	s_waitcnt lgkmcnt(1)
	v_mfma_f32_32x32x16_bf16 v[160:175], v[46:49], v[50:53], v[160:175]
	s_waitcnt lgkmcnt(0)
	s_barrier
	s_add_u32 s0, s0, 1
	s_cmp_ge_u32 s0, s13
	s_cbranch_scc1 .Lp1_drain0

.Lp2_skip20:
	ds_write_b32 v162, v33
	v_add_u32_e32 v162, 8, v162
	s_setprio 0
	s_waitcnt lgkmcnt(0)
	s_barrier
	s_branch .LBB0_1140
